# GEMM unit preambles: 128 accumulators zeroed with 64 v_mov_b64 instead of 128 v_mov_b32 (6 GEMM instances)
# speedup vs baseline: 1.0067x; 1.0067x over previous
.LBB0_252:
	s_ashr_i32 s19, s18, 31
	s_lshl_b64 s[0:1], s[18:19], 19
	s_add_u32 s20, s33, s0
	s_addc_u32 s21, s34, s1
	s_and_b64 s[0:1], s[4:5], exec
	s_cselect_b32 s19, s21, s31
	s_cselect_b32 s50, s20, s30
	s_ashr_i32 s11, s10, 31
	s_lshl_b64 s[0:1], s[10:11], 19
	s_add_u32 s22, s35, s0
	s_addc_u32 s23, s36, s1
	s_and_b64 s[0:1], s[4:5], exec
	s_cselect_b32 s11, s23, s27
	s_cselect_b32 s51, s22, s26
	s_add_u32 s0, s30, 0x40080
	s_addc_u32 s1, s31, 0
	s_add_u32 s52, s26, 0x100
	s_addc_u32 s53, s27, 0
	s_mov_b32 s54, -2
	v_mov_b64_e32 v[0:1], 0
	v_mov_b64_e32 v[2:3], 0
	v_mov_b64_e32 v[8:9], 0
	v_mov_b64_e32 v[10:11], 0
	v_mov_b64_e32 v[16:17], 0
	v_mov_b64_e32 v[18:19], 0
	v_mov_b64_e32 v[24:25], 0
	v_mov_b64_e32 v[26:27], 0
	v_mov_b64_e32 v[32:33], 0
	v_mov_b64_e32 v[34:35], 0
	v_mov_b64_e32 v[40:41], 0
	v_mov_b64_e32 v[42:43], 0
	v_mov_b64_e32 v[48:49], 0
	v_mov_b64_e32 v[50:51], 0
	v_mov_b64_e32 v[56:57], 0
	v_mov_b64_e32 v[58:59], 0
	v_mov_b64_e32 v[4:5], 0
	v_mov_b64_e32 v[6:7], 0
	v_mov_b64_e32 v[12:13], 0
	v_mov_b64_e32 v[14:15], 0
	v_mov_b64_e32 v[20:21], 0
	v_mov_b64_e32 v[22:23], 0
	v_mov_b64_e32 v[28:29], 0
	v_mov_b64_e32 v[30:31], 0
	v_mov_b64_e32 v[36:37], 0
	v_mov_b64_e32 v[38:39], 0
	v_mov_b64_e32 v[44:45], 0
	v_mov_b64_e32 v[46:47], 0
	v_mov_b64_e32 v[52:53], 0
	v_mov_b64_e32 v[54:55], 0
	v_mov_b64_e32 v[60:61], 0
	v_mov_b64_e32 v[62:63], 0
	v_mov_b64_e32 v[64:65], 0
	v_mov_b64_e32 v[66:67], 0
	v_mov_b64_e32 v[72:73], 0
	v_mov_b64_e32 v[74:75], 0
	v_mov_b64_e32 v[80:81], 0
	v_mov_b64_e32 v[82:83], 0
	v_mov_b64_e32 v[88:89], 0
	v_mov_b64_e32 v[90:91], 0
	v_mov_b64_e32 v[96:97], 0
	v_mov_b64_e32 v[98:99], 0
	v_mov_b64_e32 v[104:105], 0
	v_mov_b64_e32 v[106:107], 0
	v_mov_b64_e32 v[112:113], 0
	v_mov_b64_e32 v[114:115], 0
	v_mov_b64_e32 v[120:121], 0
	v_mov_b64_e32 v[122:123], 0
	v_mov_b64_e32 v[68:69], 0
	v_mov_b64_e32 v[70:71], 0
	v_mov_b64_e32 v[76:77], 0
	v_mov_b64_e32 v[78:79], 0
	v_mov_b64_e32 v[84:85], 0
	v_mov_b64_e32 v[86:87], 0
	v_mov_b64_e32 v[92:93], 0
	v_mov_b64_e32 v[94:95], 0
	v_mov_b64_e32 v[100:101], 0
	v_mov_b64_e32 v[102:103], 0
	v_mov_b64_e32 v[108:109], 0
	v_mov_b64_e32 v[110:111], 0
	v_mov_b64_e32 v[116:117], 0
	v_mov_b64_e32 v[118:119], 0
	v_mov_b64_e32 v[124:125], 0
	v_mov_b64_e32 v[126:127], 0
	.p2alignl 6, 3212836864

.LBB0_359:
	s_add_u32 s42, s8, 0x100
	s_addc_u32 s43, s9, 0
	s_mov_b32 s44, -2
	v_mov_b64_e32 v[0:1], 0
	v_mov_b64_e32 v[2:3], 0
	v_mov_b64_e32 v[4:5], 0
	v_mov_b64_e32 v[6:7], 0
	v_mov_b64_e32 v[16:17], 0
	v_mov_b64_e32 v[18:19], 0
	v_mov_b64_e32 v[20:21], 0
	v_mov_b64_e32 v[22:23], 0
	v_mov_b64_e32 v[32:33], 0
	v_mov_b64_e32 v[34:35], 0
	v_mov_b64_e32 v[36:37], 0
	v_mov_b64_e32 v[38:39], 0
	v_mov_b64_e32 v[48:49], 0
	v_mov_b64_e32 v[50:51], 0
	v_mov_b64_e32 v[52:53], 0
	v_mov_b64_e32 v[54:55], 0
	v_mov_b64_e32 v[8:9], 0
	v_mov_b64_e32 v[10:11], 0
	v_mov_b64_e32 v[12:13], 0
	v_mov_b64_e32 v[14:15], 0
	v_mov_b64_e32 v[24:25], 0
	v_mov_b64_e32 v[26:27], 0
	v_mov_b64_e32 v[28:29], 0
	v_mov_b64_e32 v[30:31], 0
	v_mov_b64_e32 v[40:41], 0
	v_mov_b64_e32 v[42:43], 0
	v_mov_b64_e32 v[44:45], 0
	v_mov_b64_e32 v[46:47], 0
	v_mov_b64_e32 v[56:57], 0
	v_mov_b64_e32 v[58:59], 0
	v_mov_b64_e32 v[60:61], 0
	v_mov_b64_e32 v[62:63], 0
	v_mov_b64_e32 v[64:65], 0
	v_mov_b64_e32 v[66:67], 0
	v_mov_b64_e32 v[68:69], 0
	v_mov_b64_e32 v[70:71], 0
	v_mov_b64_e32 v[80:81], 0
	v_mov_b64_e32 v[82:83], 0
	v_mov_b64_e32 v[84:85], 0
	v_mov_b64_e32 v[86:87], 0
	v_mov_b64_e32 v[96:97], 0
	v_mov_b64_e32 v[98:99], 0
	v_mov_b64_e32 v[100:101], 0
	v_mov_b64_e32 v[102:103], 0
	v_mov_b64_e32 v[112:113], 0
	v_mov_b64_e32 v[114:115], 0
	v_mov_b64_e32 v[116:117], 0
	v_mov_b64_e32 v[118:119], 0
	v_mov_b64_e32 v[72:73], 0
	v_mov_b64_e32 v[74:75], 0
	v_mov_b64_e32 v[76:77], 0
	v_mov_b64_e32 v[78:79], 0
	v_mov_b64_e32 v[88:89], 0
	v_mov_b64_e32 v[90:91], 0
	v_mov_b64_e32 v[92:93], 0
	v_mov_b64_e32 v[94:95], 0
	v_mov_b64_e32 v[104:105], 0
	v_mov_b64_e32 v[106:107], 0
	v_mov_b64_e32 v[108:109], 0
	v_mov_b64_e32 v[110:111], 0
	v_mov_b64_e32 v[120:121], 0
	v_mov_b64_e32 v[122:123], 0
	v_mov_b64_e32 v[124:125], 0
	v_mov_b64_e32 v[126:127], 0
	.p2alignl 6, 3212836864

.LBB0_587:
	s_ashr_i32 s37, s36, 31
	s_lshl_b64 s[14:15], s[36:37], 19
	s_add_u32 s38, s90, s14
	s_addc_u32 s39, s91, s15
	s_and_b64 s[14:15], s[6:7], exec
	s_cselect_b32 s9, s39, s11
	s_cselect_b32 s16, s38, s10
	s_ashr_i32 s35, s34, 31
	s_lshl_b64 s[14:15], s[34:35], 19
	s_add_u32 s40, s0, s14
	s_addc_u32 s41, s1, s15
	s_and_b64 s[14:15], s[6:7], exec
	s_cselect_b32 s17, s41, s13
	s_cselect_b32 s35, s40, s12
	s_add_u32 s10, s10, 0x40080
	s_addc_u32 s11, s11, 0
	s_add_u32 s37, s12, 0x100
	s_addc_u32 s42, s13, 0
	s_mov_b32 s43, -2
	v_mov_b64_e32 v[0:1], 0
	s_waitcnt lgkmcnt(0)
	v_mov_b64_e32 v[2:3], 0
	v_mov_b64_e32 v[4:5], 0
	v_mov_b64_e32 v[6:7], 0
	v_mov_b64_e32 v[16:17], 0
	v_mov_b64_e32 v[18:19], 0
	v_mov_b64_e32 v[20:21], 0
	v_mov_b64_e32 v[22:23], 0
	v_mov_b64_e32 v[32:33], 0
	v_mov_b64_e32 v[34:35], 0
	v_mov_b64_e32 v[36:37], 0
	v_mov_b64_e32 v[38:39], 0
	v_mov_b64_e32 v[48:49], 0
	v_mov_b64_e32 v[50:51], 0
	v_mov_b64_e32 v[52:53], 0
	v_mov_b64_e32 v[54:55], 0
	v_mov_b64_e32 v[8:9], 0
	v_mov_b64_e32 v[10:11], 0
	v_mov_b64_e32 v[12:13], 0
	v_mov_b64_e32 v[14:15], 0
	v_mov_b64_e32 v[24:25], 0
	v_mov_b64_e32 v[26:27], 0
	v_mov_b64_e32 v[28:29], 0
	v_mov_b64_e32 v[30:31], 0
	v_mov_b64_e32 v[40:41], 0
	v_mov_b64_e32 v[42:43], 0
	v_mov_b64_e32 v[44:45], 0
	v_mov_b64_e32 v[46:47], 0
	v_mov_b64_e32 v[56:57], 0
	v_mov_b64_e32 v[58:59], 0
	v_mov_b64_e32 v[60:61], 0
	v_mov_b64_e32 v[62:63], 0
	v_mov_b64_e32 v[64:65], 0
	v_mov_b64_e32 v[66:67], 0
	v_mov_b64_e32 v[68:69], 0
	v_mov_b64_e32 v[70:71], 0
	v_mov_b64_e32 v[80:81], 0
	v_mov_b64_e32 v[82:83], 0
	v_mov_b64_e32 v[84:85], 0
	v_mov_b64_e32 v[86:87], 0
	v_mov_b64_e32 v[96:97], 0
	v_mov_b64_e32 v[98:99], 0
	v_mov_b64_e32 v[100:101], 0
	v_mov_b64_e32 v[102:103], 0
	v_mov_b64_e32 v[112:113], 0
	v_mov_b64_e32 v[114:115], 0
	v_mov_b64_e32 v[116:117], 0
	v_mov_b64_e32 v[118:119], 0
	v_mov_b64_e32 v[72:73], 0
	v_mov_b64_e32 v[74:75], 0
	v_mov_b64_e32 v[76:77], 0
	v_mov_b64_e32 v[78:79], 0
	v_mov_b64_e32 v[88:89], 0
	v_mov_b64_e32 v[90:91], 0
	v_mov_b64_e32 v[92:93], 0
	v_mov_b64_e32 v[94:95], 0
	v_mov_b64_e32 v[104:105], 0
	v_mov_b64_e32 v[106:107], 0
	v_mov_b64_e32 v[108:109], 0
	v_mov_b64_e32 v[110:111], 0
	v_mov_b64_e32 v[120:121], 0
	v_mov_b64_e32 v[122:123], 0
	v_mov_b64_e32 v[124:125], 0
	v_mov_b64_e32 v[126:127], 0
	.p2alignl 6, 3212836864

.LBB0_763:
	s_ashr_i32 s21, s20, 31
	s_lshl_b64 s[22:23], s[20:21], 19
	s_add_u32 s22, s10, s22
	s_addc_u32 s23, s11, s23
	s_and_b64 s[24:25], s[8:9], exec
	s_cselect_b32 s21, s23, s27
	s_cselect_b32 s48, s22, s26
	s_ashr_i32 s19, s18, 31
	s_lshl_b64 s[24:25], s[18:19], 19
	s_add_u32 s24, s90, s24
	s_addc_u32 s25, s91, s25
	s_and_b64 s[34:35], s[8:9], exec
	s_mov_b32 s57, s49
	s_cselect_b32 s19, s25, s31
	s_cselect_b32 s49, s24, s30
	s_add_u32 s26, s26, 0x40080
	s_addc_u32 s27, s27, 0
	s_add_u32 s50, s30, 0x100
	s_addc_u32 s51, s31, 0
	s_mov_b32 s52, -2
	v_mov_b64_e32 v[0:1], 0
	v_mov_b64_e32 v[2:3], 0
	v_mov_b64_e32 v[32:33], 0
	v_mov_b64_e32 v[34:35], 0
	v_mov_b64_e32 v[4:5], 0
	v_mov_b64_e32 v[6:7], 0
	v_mov_b64_e32 v[36:37], 0
	v_mov_b64_e32 v[38:39], 0
	v_mov_b64_e32 v[8:9], 0
	v_mov_b64_e32 v[10:11], 0
	v_mov_b64_e32 v[40:41], 0
	v_mov_b64_e32 v[42:43], 0
	v_mov_b64_e32 v[12:13], 0
	v_mov_b64_e32 v[14:15], 0
	v_mov_b64_e32 v[44:45], 0
	v_mov_b64_e32 v[46:47], 0
	v_mov_b64_e32 v[64:65], 0
	v_mov_b64_e32 v[66:67], 0
	v_mov_b64_e32 v[96:97], 0
	v_mov_b64_e32 v[98:99], 0
	v_mov_b64_e32 v[68:69], 0
	v_mov_b64_e32 v[70:71], 0
	v_mov_b64_e32 v[100:101], 0
	v_mov_b64_e32 v[102:103], 0
	v_mov_b64_e32 v[72:73], 0
	v_mov_b64_e32 v[74:75], 0
	v_mov_b64_e32 v[104:105], 0
	v_mov_b64_e32 v[106:107], 0
	v_mov_b64_e32 v[76:77], 0
	v_mov_b64_e32 v[78:79], 0
	v_mov_b64_e32 v[108:109], 0
	v_mov_b64_e32 v[110:111], 0
	v_mov_b64_e32 v[16:17], 0
	v_mov_b64_e32 v[18:19], 0
	v_mov_b64_e32 v[48:49], 0
	v_mov_b64_e32 v[50:51], 0
	v_mov_b64_e32 v[20:21], 0
	v_mov_b64_e32 v[22:23], 0
	v_mov_b64_e32 v[52:53], 0
	v_mov_b64_e32 v[54:55], 0
	v_mov_b64_e32 v[24:25], 0
	v_mov_b64_e32 v[26:27], 0
	v_mov_b64_e32 v[56:57], 0
	v_mov_b64_e32 v[58:59], 0
	v_mov_b64_e32 v[28:29], 0
	v_mov_b64_e32 v[30:31], 0
	v_mov_b64_e32 v[60:61], 0
	v_mov_b64_e32 v[62:63], 0
	v_mov_b64_e32 v[80:81], 0
	v_mov_b64_e32 v[82:83], 0
	v_mov_b64_e32 v[112:113], 0
	v_mov_b64_e32 v[114:115], 0
	v_mov_b64_e32 v[84:85], 0
	v_mov_b64_e32 v[86:87], 0
	v_mov_b64_e32 v[116:117], 0
	v_mov_b64_e32 v[118:119], 0
	v_mov_b64_e32 v[88:89], 0
	v_mov_b64_e32 v[90:91], 0
	v_mov_b64_e32 v[120:121], 0
	v_mov_b64_e32 v[122:123], 0
	v_mov_b64_e32 v[92:93], 0
	v_mov_b64_e32 v[94:95], 0
	v_mov_b64_e32 v[124:125], 0
	v_mov_b64_e32 v[126:127], 0
	.p2alignl 6, 3212836864

.LBB0_1334:
	s_ashr_i32 s17, s16, 31
	s_lshl_b64 s[18:19], s[16:17], 18
	s_add_u32 s18, s33, s18
	s_addc_u32 s19, s34, s19
	s_and_b64 s[20:21], s[6:7], exec
	s_cselect_b32 s17, s19, s9
	s_cselect_b32 s49, s18, s8
	s_ashr_i32 s15, s14, 31
	s_lshl_b64 s[20:21], s[14:15], 18
	s_add_u32 s20, s35, s20
	s_addc_u32 s21, s36, s21
	s_and_b64 s[24:25], s[6:7], exec
	s_cselect_b32 s15, s21, s23
	s_cselect_b32 s50, s20, s22
	s_add_u32 s8, s8, 0x20080
	s_addc_u32 s9, s9, 0
	s_add_u32 s51, s22, 0x100
	s_addc_u32 s52, s23, 0
	s_mov_b32 s53, -2
	v_mov_b64_e32 v[0:1], 0
	v_mov_b64_e32 v[2:3], 0
	v_mov_b64_e32 v[4:5], 0
	v_mov_b64_e32 v[6:7], 0
	v_mov_b64_e32 v[16:17], 0
	v_mov_b64_e32 v[18:19], 0
	v_mov_b64_e32 v[20:21], 0
	v_mov_b64_e32 v[22:23], 0
	v_mov_b64_e32 v[32:33], 0
	v_mov_b64_e32 v[34:35], 0
	v_mov_b64_e32 v[36:37], 0
	v_mov_b64_e32 v[38:39], 0
	v_mov_b64_e32 v[48:49], 0
	v_mov_b64_e32 v[50:51], 0
	v_mov_b64_e32 v[52:53], 0
	v_mov_b64_e32 v[54:55], 0
	v_mov_b64_e32 v[8:9], 0
	v_mov_b64_e32 v[10:11], 0
	v_mov_b64_e32 v[12:13], 0
	v_mov_b64_e32 v[14:15], 0
	v_mov_b64_e32 v[24:25], 0
	v_mov_b64_e32 v[26:27], 0
	v_mov_b64_e32 v[28:29], 0
	v_mov_b64_e32 v[30:31], 0
	v_mov_b64_e32 v[40:41], 0
	v_mov_b64_e32 v[42:43], 0
	v_mov_b64_e32 v[44:45], 0
	v_mov_b64_e32 v[46:47], 0
	v_mov_b64_e32 v[56:57], 0
	v_mov_b64_e32 v[58:59], 0
	v_mov_b64_e32 v[60:61], 0
	v_mov_b64_e32 v[62:63], 0
	v_mov_b64_e32 v[64:65], 0
	v_mov_b64_e32 v[66:67], 0
	v_mov_b64_e32 v[68:69], 0
	v_mov_b64_e32 v[70:71], 0
	v_mov_b64_e32 v[80:81], 0
	v_mov_b64_e32 v[82:83], 0
	v_mov_b64_e32 v[84:85], 0
	v_mov_b64_e32 v[86:87], 0
	v_mov_b64_e32 v[96:97], 0
	v_mov_b64_e32 v[98:99], 0
	v_mov_b64_e32 v[100:101], 0
	v_mov_b64_e32 v[102:103], 0
	v_mov_b64_e32 v[112:113], 0
	v_mov_b64_e32 v[114:115], 0
	v_mov_b64_e32 v[116:117], 0
	v_mov_b64_e32 v[118:119], 0
	v_mov_b64_e32 v[72:73], 0
	v_mov_b64_e32 v[74:75], 0
	v_mov_b64_e32 v[76:77], 0
	v_mov_b64_e32 v[78:79], 0
	v_mov_b64_e32 v[88:89], 0
	v_mov_b64_e32 v[90:91], 0
	v_mov_b64_e32 v[92:93], 0
	v_mov_b64_e32 v[94:95], 0
	v_mov_b64_e32 v[104:105], 0
	v_mov_b64_e32 v[106:107], 0
	v_mov_b64_e32 v[108:109], 0
	v_mov_b64_e32 v[110:111], 0
	v_mov_b64_e32 v[120:121], 0
	v_mov_b64_e32 v[122:123], 0
	v_mov_b64_e32 v[124:125], 0
	v_mov_b64_e32 v[126:127], 0
	.p2alignl 6, 3212836864

.LBB0_1437:
	s_ashr_i32 s13, s12, 31
	s_lshl_b64 s[14:15], s[12:13], 19
	s_add_u32 s14, s24, s14
	s_addc_u32 s15, s25, s15
	s_and_b64 s[16:17], s[4:5], exec
	s_cselect_b32 s13, s15, s19
	s_cselect_b32 s44, s14, s18
	s_ashr_i32 s11, s10, 31
	s_lshl_b64 s[16:17], s[10:11], 19
	s_add_u32 s16, s26, s16
	s_addc_u32 s17, s27, s17
	s_and_b64 s[22:23], s[4:5], exec
	s_cselect_b32 s11, s17, s21
	s_cselect_b32 s45, s16, s20
	s_add_u32 s18, s18, 0x40080
	s_addc_u32 s19, s19, 0
	s_add_u32 s46, s20, 0x100
	s_mov_b32 s53, s49
	s_addc_u32 s47, s21, 0
	s_mov_b32 s48, -2
	v_mov_b64_e32 v[0:1], 0
	v_mov_b64_e32 v[2:3], 0
	v_mov_b64_e32 v[4:5], 0
	v_mov_b64_e32 v[6:7], 0
	v_mov_b64_e32 v[16:17], 0
	v_mov_b64_e32 v[18:19], 0
	v_mov_b64_e32 v[20:21], 0
	v_mov_b64_e32 v[22:23], 0
	v_mov_b64_e32 v[32:33], 0
	v_mov_b64_e32 v[34:35], 0
	v_mov_b64_e32 v[36:37], 0
	v_mov_b64_e32 v[38:39], 0
	v_mov_b64_e32 v[48:49], 0
	v_mov_b64_e32 v[50:51], 0
	v_mov_b64_e32 v[52:53], 0
	v_mov_b64_e32 v[54:55], 0
	v_mov_b64_e32 v[8:9], 0
	v_mov_b64_e32 v[10:11], 0
	v_mov_b64_e32 v[12:13], 0
	v_mov_b64_e32 v[14:15], 0
	v_mov_b64_e32 v[24:25], 0
	v_mov_b64_e32 v[26:27], 0
	v_mov_b64_e32 v[28:29], 0
	v_mov_b64_e32 v[30:31], 0
	v_mov_b64_e32 v[40:41], 0
	v_mov_b64_e32 v[42:43], 0
	v_mov_b64_e32 v[44:45], 0
	v_mov_b64_e32 v[46:47], 0
	v_mov_b64_e32 v[56:57], 0
	v_mov_b64_e32 v[58:59], 0
	v_mov_b64_e32 v[60:61], 0
	v_mov_b64_e32 v[62:63], 0
	v_mov_b64_e32 v[64:65], 0
	v_mov_b64_e32 v[66:67], 0
	v_mov_b64_e32 v[68:69], 0
	v_mov_b64_e32 v[70:71], 0
	v_mov_b64_e32 v[80:81], 0
	v_mov_b64_e32 v[82:83], 0
	v_mov_b64_e32 v[84:85], 0
	v_mov_b64_e32 v[86:87], 0
	v_mov_b64_e32 v[96:97], 0
	v_mov_b64_e32 v[98:99], 0
	v_mov_b64_e32 v[100:101], 0
	v_mov_b64_e32 v[102:103], 0
	v_mov_b64_e32 v[112:113], 0
	v_mov_b64_e32 v[114:115], 0
	v_mov_b64_e32 v[116:117], 0
	v_mov_b64_e32 v[118:119], 0
	v_mov_b64_e32 v[72:73], 0
	v_mov_b64_e32 v[74:75], 0
	v_mov_b64_e32 v[76:77], 0
	v_mov_b64_e32 v[78:79], 0
	v_mov_b64_e32 v[88:89], 0
	v_mov_b64_e32 v[90:91], 0
	v_mov_b64_e32 v[92:93], 0
	v_mov_b64_e32 v[94:95], 0
	v_mov_b64_e32 v[104:105], 0
	v_mov_b64_e32 v[106:107], 0
	v_mov_b64_e32 v[108:109], 0
	v_mov_b64_e32 v[110:111], 0
	v_mov_b64_e32 v[120:121], 0
	v_mov_b64_e32 v[122:123], 0
	v_mov_b64_e32 v[124:125], 0
	v_mov_b64_e32 v[126:127], 0
	.p2alignl 6, 3212836864
